# shift@W GEMV of phase 2 skipped by the blocks that carry a 4th GEMM tile
# speedup vs baseline: 1.0545x; 1.0022x over previous
.LBB0_178:
	s_and_b64 vcc, exec, s[0:1]
	s_cbranch_vccz .LBB0_382
	v_readlane_b32 s0, v248, 19
	s_mov_b32 s59, s52
	s_cmp_gt_u32 s0, 4
	v_readlane_b32 s1, v248, 20
	s_cbranch_scc1 .LBB0_192
	s_waitcnt lgkmcnt(11)
	v_mov_b32_e32 v3, v0
	v_readlane_b32 s0, v248, 41
	v_readlane_b32 s1, v246, 41
	s_nop 1
	s_cmp_eq_u32 s1, 0x200
	s_cbranch_scc0 .Lsw_std
	s_cmp_lt_u32 s0, 0x100
	s_cbranch_scc1 .LBB0_192
	s_sub_u32 s0, s0, 0x100
.Lsw_std:
	v_ashrrev_i32_e32 v2, 6, v3
	s_nop 0
	v_add_u32_e32 v2, s0, v2
	s_movk_i32 s0, 0x1a00
	v_cmp_gt_i32_e32 vcc, s0, v2
	s_and_saveexec_b64 s[0:1], vcc
	s_cbranch_execz .LBB0_191
	v_readlane_b32 s20, v248, 42
	v_readlane_b32 s21, v248, 43
	v_and_b32_e32 v3, 63, v3
	v_cmp_lt_i32_e32 vcc, v162, v161
	s_load_dword s2, s[20:21], 0x0
	s_waitcnt lgkmcnt(0)
	v_lshlrev_b32_e32 v6, 4, v3
	v_lshlrev_b32_e32 v146, 6, v3
	v_cmp_eq_u32_e64 s[36:37], 0, v3
	v_cndmask_b32_e32 v3, v160, v162, vcc
	v_cmp_lt_i32_e32 vcc, v163, v161
	v_lshlrev_b32_e32 v16, 2, v3
	s_waitcnt lgkmcnt(0)
	s_lshl_b32 s20, s2, 2
	s_cmp_eq_u32 s2, 0x200
	s_cselect_b32 s20, 0x700, s20
	v_cndmask_b32_e32 v3, v160, v163, vcc
	v_cmp_lt_i32_e32 vcc, v164, v161
	v_lshlrev_b32_e32 v17, 2, v3
	v_lshl_add_u64 v[4:5], s[4:5], 0, v[146:147]
	v_cndmask_b32_e32 v3, v160, v164, vcc
	v_cmp_lt_i32_e32 vcc, v165, v161
	v_lshlrev_b32_e32 v18, 2, v3
	s_ashr_i32 s21, s20, 31
	v_cndmask_b32_e32 v3, v160, v165, vcc
	v_cmp_lt_i32_e32 vcc, v166, v161
	v_lshlrev_b32_e32 v19, 2, v3
	s_mov_b64 s[22:23], 0
	v_cndmask_b32_e32 v3, v160, v166, vcc
	v_cmp_lt_i32_e32 vcc, v167, v161
	v_lshlrev_b32_e32 v20, 2, v3
	v_lshlrev_b32_e32 v6, 1, v6
	v_cndmask_b32_e32 v3, v160, v167, vcc
	v_lshlrev_b32_e32 v21, 2, v3
	v_ashrrev_i32_e32 v3, 31, v2
	s_branch .LBB0_183
